# combines scalar tile-limit test and scalar-base K/V tile loads with the previous best
# baseline (speedup 1.0000x reference)
; template <int NS>
; __device__ __forceinline__ void attn_unit(const AUnit& u, unsigned char* lds, const bf16_t* __restrict__ GT, bf16_t* BRc, float sc, float lam, const float* __restrict__ subln) {
;     const int tid = threadIdx.x, wid = tid >> 6, lane = tid & 63, l31 = lane & 31, hh = lane >> 5;
;     const bool active = wid < u.nqw;
;     const int limit = u.causal ? u.lim0 + (wid >> 1) : u.ntiles;
;     const int qrow = u.qrow0 + wid * 32 + l31;
;     unsigned char* qs = lds + 2 * A_BUF + wid * (32 * A_KRS);
;     if (active) {
;         const bf16_t* qp = BRc + (size_t)qrow * BR + u.qcol + hh * 64;
; #pragma unroll
;         for (int i = 0; i < 8; ++i) *(u32x4*)(qs + l31 * A_KRS + hh * 128 + i * 16) = *(const u32x4*)(qp + i * 8);
;     }
;     const unsigned char* q_rd = qs + l31 * A_KRS + hh * 16;
;     f32x16 O0[4], O1[4];
;     float m0 = -1e30f, m1 = -1e30f, l0r = 0.f, l1r = 0.f;
; #pragma unroll
;     for (int d = 0; d < 4; ++d)
; #pragma unroll
;         for (int r = 0; r < 16; ++r) { O0[d][r] = 0.f; O1[d][r] = 0.f; }
;     u32x4 rk[2], rv[2];
;     attn_load1(u.kb, u.ld, 0, rk); attn_load1(u.vb, u.ld, 0, rv);
;     attn_store1(lds, A_KRS, rk); attn_store1(lds + A_KT, A_VRS, rv);
;     __syncthreads();
.LBB0_1159:
	s_or_b64 exec, exec, s[12:13]
	v_add_u32_e32 v16, s14, v208
	v_mov_b32_e32 v17, s77
	v_sub_u32_e32 v18, s15, v217
	v_mov_b32_e32 v14, v181
	v_mov_b32_e32 v15, v181
	v_mov_b32_e32 v0, v181
	v_mov_b32_e32 v1, v181
	v_mov_b32_e32 v2, v181
	v_mov_b32_e32 v3, v181
	v_mov_b32_e32 v4, v181
	v_mov_b32_e32 v5, v181
	v_mov_b32_e32 v6, v181
	v_mov_b32_e32 v7, v181
	v_mov_b32_e32 v8, v181
	v_mov_b32_e32 v9, v181
	v_mov_b32_e32 v10, v181
	v_mov_b32_e32 v11, v181
	v_mov_b32_e32 v12, v181
	v_mov_b32_e32 v13, v181
	v_cndmask_b32_e64 v193, v16, v17, s[4:5]
	s_mov_b64 s[86:87], s[10:11]
	s_mov_b64 s[90:91], s[8:9]
	v_cmp_lt_u32_e64 s[8:9], 32, v18
	v_readfirstlane_b32 s85, v193
	v_cmp_lt_u32_e64 s[10:11], 33, v18
	v_cmp_lt_u32_e64 s[12:13], 34, v18
	v_cmp_lt_u32_e64 s[14:15], 35, v18
	v_cmp_lt_u32_e64 s[16:17], 40, v18
	v_cmp_lt_u32_e64 s[18:19], 41, v18
	v_cmp_lt_u32_e64 s[20:21], 42, v18
	v_cmp_lt_u32_e64 s[22:23], 43, v18
	v_cmp_lt_u32_e64 s[24:25], 48, v18
	v_cmp_lt_u32_e64 s[26:27], 49, v18
	v_cmp_lt_u32_e64 s[28:29], 50, v18
	v_cmp_lt_u32_e64 s[30:31], 51, v18
	v_cmp_lt_u32_e64 s[34:35], 56, v18
	v_cmp_lt_u32_e64 s[36:37], 57, v18
	v_cmp_lt_u32_e64 s[38:39], 58, v18
	v_cmp_lt_u32_e64 s[40:41], 59, v18
	v_mov_b64_e32 v[46:47], v[14:15]
	v_mov_b64_e32 v[62:63], v[14:15]
	v_mov_b64_e32 v[78:79], v[14:15]
	v_mov_b64_e32 v[30:31], v[14:15]
	v_mov_b64_e32 v[94:95], v[14:15]
	v_mov_b64_e32 v[110:111], v[14:15]
	v_mov_b64_e32 v[126:127], v[14:15]
	v_add_u32_e32 v136, v212, v213
	s_add_i32 s61, s77, -1
	s_mov_b32 s42, 0
	v_mov_b32_e32 v228, 0xf149f2ca
	v_mov_b32_e32 v226, 0
	v_mov_b32_e32 v189, v177
	v_mov_b32_e32 v191, v175
	v_mov_b32_e32 v227, 0
	v_mov_b64_e32 v[44:45], v[12:13]
	v_mov_b64_e32 v[42:43], v[10:11]
	v_mov_b64_e32 v[40:41], v[8:9]
	v_mov_b64_e32 v[38:39], v[6:7]
	v_mov_b64_e32 v[36:37], v[4:5]
	v_mov_b64_e32 v[34:35], v[2:3]
	v_mov_b64_e32 v[32:33], v[0:1]
	v_mov_b64_e32 v[60:61], v[12:13]
	v_mov_b64_e32 v[58:59], v[10:11]
	v_mov_b64_e32 v[56:57], v[8:9]
	v_mov_b64_e32 v[54:55], v[6:7]
	v_mov_b64_e32 v[52:53], v[4:5]
	v_mov_b64_e32 v[50:51], v[2:3]
	v_mov_b64_e32 v[48:49], v[0:1]
	v_mov_b64_e32 v[76:77], v[12:13]
	v_mov_b64_e32 v[74:75], v[10:11]
	v_mov_b64_e32 v[72:73], v[8:9]
	v_mov_b64_e32 v[70:71], v[6:7]
	v_mov_b64_e32 v[68:69], v[4:5]
	v_mov_b64_e32 v[66:67], v[2:3]
	v_mov_b64_e32 v[64:65], v[0:1]
	v_mov_b64_e32 v[28:29], v[12:13]
	v_mov_b64_e32 v[26:27], v[10:11]
	v_mov_b64_e32 v[24:25], v[8:9]
	v_mov_b64_e32 v[22:23], v[6:7]
	v_mov_b64_e32 v[20:21], v[4:5]
	v_mov_b64_e32 v[18:19], v[2:3]
	v_mov_b64_e32 v[16:17], v[0:1]
	v_mov_b64_e32 v[92:93], v[12:13]
	v_mov_b64_e32 v[90:91], v[10:11]
	v_mov_b64_e32 v[88:89], v[8:9]
	v_mov_b64_e32 v[86:87], v[6:7]
	v_mov_b64_e32 v[84:85], v[4:5]
	v_mov_b64_e32 v[82:83], v[2:3]
	v_mov_b64_e32 v[80:81], v[0:1]
	v_mov_b64_e32 v[108:109], v[12:13]
	v_mov_b64_e32 v[106:107], v[10:11]
	v_mov_b64_e32 v[104:105], v[8:9]
	v_mov_b64_e32 v[102:103], v[6:7]
	v_mov_b64_e32 v[100:101], v[4:5]
	v_mov_b64_e32 v[98:99], v[2:3]
	v_mov_b64_e32 v[96:97], v[0:1]
	v_mov_b64_e32 v[124:125], v[12:13]
	v_mov_b64_e32 v[122:123], v[10:11]
	v_mov_b64_e32 v[120:121], v[8:9]
	v_mov_b64_e32 v[118:119], v[6:7]
	v_mov_b64_e32 v[116:117], v[4:5]
	v_mov_b64_e32 v[114:115], v[2:3]
	v_mov_b64_e32 v[112:113], v[0:1]
	v_mov_b32_e32 v229, 0xf149f2ca
	v_add_u32_e32 v137, v212, v214
	v_add_u32_e32 v138, v212, v215
	v_add_u32_e32 v139, v212, v216
	s_waitcnt vmcnt(3)
	ds_write_b128 v136, v[160:163]
	s_waitcnt vmcnt(2)
	ds_write_b128 v137, v[164:167]
	s_waitcnt vmcnt(1)
	ds_write_b128 v138, v[128:131] offset:17408
	s_waitcnt vmcnt(0)
	ds_write_b128 v139, v[132:135] offset:17408
	s_waitcnt lgkmcnt(0)
	s_barrier
